# comb8 + SwiGLU gate/up epilogue with packed f32 mul/add (same per-element formula), row addresses precomputed
# speedup vs baseline: 1.0049x; 1.0049x over previous
; __device__ __forceinline__ unsigned cvt_pk(float lo, float hi) { unsigned r; asm volatile("v_cvt_pk_bf16_f32 %0, %1, %2" : "=v"(r) : "v"(lo), "v"(hi)); return r; }
;     __device__ __forceinline__ void operator()(const Acc& acc, const Unit& u, int wr, int wc, int fr, int fq) const {
;         const size_t Rb = (size_t)u.pb * NT + u.pm * 256 + wr * 64 + fr; const int col0 = u.pn * 128 + wc * 32 + 8 * fq;
; #pragma unroll
;         for (int ai = 0; ai < 2; ++ai)
; #pragma unroll
;             for (int m = 0; m < 4; ++m) { bf16_t* rowp = H + (Rb + ai * 128 + m * 16) * FF + col0; f32x4 v[2];
; #pragma unroll
;                 for (int n = 0; n < 2; ++n) { const f32x4 gt = acc[ai][0][m][n], up = acc[ai][1][m][n];
; #pragma unroll
;                     for (int i = 0; i < 4; ++i) v[n][i] = gt[i] * __builtin_amdgcn_rcpf(1.f + __builtin_amdgcn_exp2f(-1.4426950408889634f * gt[i])) * up[i]; }
;                 u32x4 w; w.x = cvt_pk(v[0][0], v[0][1]); w.y = cvt_pk(v[0][2], v[0][3]); w.z = cvt_pk(v[1][0], v[1][1]); w.w = cvt_pk(v[1][2], v[1][3]); *(u32x4*)rowp = w; }
;     }
.LBB0_1061:
	s_lshl_b32 s17, s36, 8
	s_lshl_b32 s24, s24, 7
	s_ashr_i32 s19, s17, 31
	s_or_b32 s24, s24, s56
	s_add_u32 s17, s17, s55
	s_mul_i32 s5, s73, 0x900
	s_addc_u32 s19, s19, s59
	v_mov_b32_e32 v153, v146
	s_add_u32 s5, s17, s5
	s_mul_hi_i32 s4, s73, 0x900
	v_and_or_b32 v156, v153, 15, s5
	v_mov_b64_e32 v[154:155], s[10:11]
	s_addc_u32 s17, s19, s4
	v_mad_u64_u32 v[154:155], s[4:5], v156, s66, v[154:155]
	v_ashrrev_i32_e32 v152, 1, v153
	v_and_b32_e32 v152, -8, v152
	v_add_u32_e32 v152, s24, v152
	v_ashrrev_i32_e32 v153, 31, v152
	v_mad_i32_i24 v155, s17, v151, v155
	v_lshl_add_u64 v[158:159], v[152:153], 1, v[154:155]
	s_mov_b32 s98, 0xbfb8aa3b
	s_mov_b32 s99, 0xbfb8aa3b
	s_mov_b32 s100, 1.0
	s_mov_b32 s101, 1.0
	v_add_co_u32_e32 v186, vcc, 0x16000, v158
	s_nop 1
	v_addc_co_u32_e32 v187, vcc, 0, v159, vcc
	v_add_co_u32_e32 v188, vcc, 0x2c000, v158
	s_nop 1
	v_addc_co_u32_e32 v189, vcc, 0, v159, vcc
	v_add_co_u32_e32 v190, vcc, 0x42000, v158
	s_nop 1
	v_addc_co_u32_e32 v191, vcc, 0, v159, vcc
	v_add_co_u32_e32 v192, vcc, 0xb0000, v158
	s_nop 1
	v_addc_co_u32_e32 v193, vcc, 0, v159, vcc
	v_add_co_u32_e32 v194, vcc, 0xc6000, v158
	s_nop 1
	v_addc_co_u32_e32 v195, vcc, 0, v159, vcc
	v_add_co_u32_e32 v196, vcc, 0xdc000, v158
	s_nop 1
	v_addc_co_u32_e32 v197, vcc, 0, v159, vcc
	v_add_co_u32_e32 v198, vcc, 0xf2000, v158
	s_nop 1
	v_addc_co_u32_e32 v199, vcc, 0, v159, vcc
	v_pk_mul_f32 v[160:161], v[126:127], s[98:99]
	v_pk_mul_f32 v[162:163], v[128:129], s[98:99]
	v_pk_mul_f32 v[164:165], v[122:123], s[98:99]
	v_pk_mul_f32 v[166:167], v[124:125], s[98:99]
	v_exp_f32_e32 v160, v160
	v_exp_f32_e32 v161, v161
	v_exp_f32_e32 v162, v162
	v_exp_f32_e32 v163, v163
	v_exp_f32_e32 v164, v164
	v_exp_f32_e32 v165, v165
	v_exp_f32_e32 v166, v166
	v_exp_f32_e32 v167, v167
	v_pk_add_f32 v[160:161], v[160:161], s[100:101]
	v_pk_add_f32 v[162:163], v[162:163], s[100:101]
	v_pk_add_f32 v[164:165], v[164:165], s[100:101]
	v_pk_add_f32 v[166:167], v[166:167], s[100:101]
	v_rcp_f32_e32 v160, v160
	v_rcp_f32_e32 v161, v161
	v_rcp_f32_e32 v162, v162
	v_rcp_f32_e32 v163, v163
	v_rcp_f32_e32 v164, v164
	v_rcp_f32_e32 v165, v165
	v_rcp_f32_e32 v166, v166
	v_rcp_f32_e32 v167, v167
	v_pk_mul_f32 v[160:161], v[126:127], v[160:161]
	v_pk_mul_f32 v[162:163], v[128:129], v[162:163]
	v_pk_mul_f32 v[164:165], v[122:123], v[164:165]
	v_pk_mul_f32 v[166:167], v[124:125], v[166:167]
	v_pk_mul_f32 v[160:161], v[160:161], v[118:119]
	v_pk_mul_f32 v[162:163], v[162:163], v[120:121]
	v_pk_mul_f32 v[164:165], v[164:165], v[114:115]
	v_pk_mul_f32 v[166:167], v[166:167], v[116:117]
	v_cvt_pk_bf16_f32 v176, v160, v161
	v_cvt_pk_bf16_f32 v177, v162, v163
	v_cvt_pk_bf16_f32 v178, v164, v165
	v_cvt_pk_bf16_f32 v179, v166, v167
	global_store_dwordx4 v[158:159], v[176:179], off
	v_pk_mul_f32 v[168:169], v[110:111], s[98:99]
	v_pk_mul_f32 v[170:171], v[112:113], s[98:99]
	v_pk_mul_f32 v[172:173], v[106:107], s[98:99]
	v_pk_mul_f32 v[174:175], v[108:109], s[98:99]
	v_exp_f32_e32 v168, v168
	v_exp_f32_e32 v169, v169
	v_exp_f32_e32 v170, v170
	v_exp_f32_e32 v171, v171
	v_exp_f32_e32 v172, v172
	v_exp_f32_e32 v173, v173
	v_exp_f32_e32 v174, v174
	v_exp_f32_e32 v175, v175
	v_pk_add_f32 v[168:169], v[168:169], s[100:101]
	v_pk_add_f32 v[170:171], v[170:171], s[100:101]
	v_pk_add_f32 v[172:173], v[172:173], s[100:101]
	v_pk_add_f32 v[174:175], v[174:175], s[100:101]
	v_rcp_f32_e32 v168, v168
	v_rcp_f32_e32 v169, v169
	v_rcp_f32_e32 v170, v170
	v_rcp_f32_e32 v171, v171
	v_rcp_f32_e32 v172, v172
	v_rcp_f32_e32 v173, v173
	v_rcp_f32_e32 v174, v174
	v_rcp_f32_e32 v175, v175
	v_pk_mul_f32 v[168:169], v[110:111], v[168:169]
	v_pk_mul_f32 v[170:171], v[112:113], v[170:171]
	v_pk_mul_f32 v[172:173], v[106:107], v[172:173]
	v_pk_mul_f32 v[174:175], v[108:109], v[174:175]
	v_pk_mul_f32 v[168:169], v[168:169], v[102:103]
	v_pk_mul_f32 v[170:171], v[170:171], v[104:105]
	v_pk_mul_f32 v[172:173], v[172:173], v[98:99]
	v_pk_mul_f32 v[174:175], v[174:175], v[100:101]
	v_cvt_pk_bf16_f32 v180, v168, v169
	v_cvt_pk_bf16_f32 v181, v170, v171
	v_cvt_pk_bf16_f32 v182, v172, v173
	v_cvt_pk_bf16_f32 v183, v174, v175
	global_store_dwordx4 v[186:187], v[180:183], off
	v_pk_mul_f32 v[160:161], v[94:95], s[98:99]
	v_pk_mul_f32 v[162:163], v[96:97], s[98:99]
	v_pk_mul_f32 v[164:165], v[90:91], s[98:99]
	v_pk_mul_f32 v[166:167], v[92:93], s[98:99]
	v_exp_f32_e32 v160, v160
	v_exp_f32_e32 v161, v161
	v_exp_f32_e32 v162, v162
	v_exp_f32_e32 v163, v163
	v_exp_f32_e32 v164, v164
	v_exp_f32_e32 v165, v165
	v_exp_f32_e32 v166, v166
	v_exp_f32_e32 v167, v167
	v_pk_add_f32 v[160:161], v[160:161], s[100:101]
	v_pk_add_f32 v[162:163], v[162:163], s[100:101]
	v_pk_add_f32 v[164:165], v[164:165], s[100:101]
	v_pk_add_f32 v[166:167], v[166:167], s[100:101]
	v_rcp_f32_e32 v160, v160
	v_rcp_f32_e32 v161, v161
	v_rcp_f32_e32 v162, v162
	v_rcp_f32_e32 v163, v163
	v_rcp_f32_e32 v164, v164
	v_rcp_f32_e32 v165, v165
	v_rcp_f32_e32 v166, v166
	v_rcp_f32_e32 v167, v167
	v_pk_mul_f32 v[160:161], v[94:95], v[160:161]
	v_pk_mul_f32 v[162:163], v[96:97], v[162:163]
	v_pk_mul_f32 v[164:165], v[90:91], v[164:165]
	v_pk_mul_f32 v[166:167], v[92:93], v[166:167]
	v_pk_mul_f32 v[160:161], v[160:161], v[86:87]
	v_pk_mul_f32 v[162:163], v[162:163], v[88:89]
	v_pk_mul_f32 v[164:165], v[164:165], v[82:83]
	v_pk_mul_f32 v[166:167], v[166:167], v[84:85]
	v_cvt_pk_bf16_f32 v176, v160, v161
	v_cvt_pk_bf16_f32 v177, v162, v163
	v_cvt_pk_bf16_f32 v178, v164, v165
	v_cvt_pk_bf16_f32 v179, v166, v167
	global_store_dwordx4 v[188:189], v[176:179], off
	v_pk_mul_f32 v[168:169], v[78:79], s[98:99]
	v_pk_mul_f32 v[170:171], v[80:81], s[98:99]
	v_pk_mul_f32 v[172:173], v[74:75], s[98:99]
; __device__ __forceinline__ unsigned cvt_pk(float lo, float hi) { unsigned r; asm volatile("v_cvt_pk_bf16_f32 %0, %1, %2" : "=v"(r) : "v"(lo), "v"(hi)); return r; }
; #define PG8_BAR __builtin_amdgcn_s_barrier()
; template <class Epi>
; __device__ __forceinline__ void gemm_phase(LAS unsigned char* lds, const Gemm g, int G, int c, const Epi& E) {
;     ...
;         if (!has_next) break;
; #pragma unroll
;         for (int a = 0; a < 2; ++a)
; #pragma unroll
;             for (int b = 0; b < 2; ++b)
; #pragma unroll
;                 for (int m = 0; m < 4; ++m)
; #pragma unroll
;                     for (int n = 0; n < 2; ++n) acc[a][b][m][n] = (f32x4){0.f, 0.f, 0.f, 0.f};
;         cur = nxt; cA = nA; cB = nB; ++ui;
;         if (wr == 1) PG8_BAR;
;     __device__ __forceinline__ void operator()(const Acc& acc, const Unit& u, int wr, int wc, int fr, int fq) const {
;         const size_t Rb = (size_t)u.pb * NT + u.pm * 256 + wr * 64 + fr; const int col0 = u.pn * 128 + wc * 32 + 8 * fq;
; #pragma unroll
;         for (int ai = 0; ai < 2; ++ai)
; #pragma unroll
;             for (int m = 0; m < 4; ++m) { bf16_t* rowp = H + (Rb + ai * 128 + m * 16) * FF + col0; f32x4 v[2];
; #pragma unroll
;                 for (int n = 0; n < 2; ++n) { const f32x4 gt = acc[ai][0][m][n], up = acc[ai][1][m][n];
; #pragma unroll
;                     for (int i = 0; i < 4; ++i) v[n][i] = gt[i] * __builtin_amdgcn_rcpf(1.f + __builtin_amdgcn_exp2f(-1.4426950408889634f * gt[i])) * up[i]; }
;                 u32x4 w; w.x = cvt_pk(v[0][0], v[0][1]); w.y = cvt_pk(v[0][2], v[0][3]); w.z = cvt_pk(v[1][0], v[1][1]); w.w = cvt_pk(v[1][2], v[1][3]); *(u32x4*)rowp = w; }
;     }
	v_pk_mul_f32 v[174:175], v[76:77], s[98:99]
	v_exp_f32_e32 v168, v168
	v_exp_f32_e32 v169, v169
	v_exp_f32_e32 v170, v170
	v_exp_f32_e32 v171, v171
	v_exp_f32_e32 v172, v172
	v_exp_f32_e32 v173, v173
	v_exp_f32_e32 v174, v174
	v_exp_f32_e32 v175, v175
	v_pk_add_f32 v[168:169], v[168:169], s[100:101]
	v_pk_add_f32 v[170:171], v[170:171], s[100:101]
	v_pk_add_f32 v[172:173], v[172:173], s[100:101]
	v_pk_add_f32 v[174:175], v[174:175], s[100:101]
	v_rcp_f32_e32 v168, v168
	v_rcp_f32_e32 v169, v169
	v_rcp_f32_e32 v170, v170
	v_rcp_f32_e32 v171, v171
	v_rcp_f32_e32 v172, v172
	v_rcp_f32_e32 v173, v173
	v_rcp_f32_e32 v174, v174
	v_rcp_f32_e32 v175, v175
	v_pk_mul_f32 v[168:169], v[78:79], v[168:169]
	v_pk_mul_f32 v[170:171], v[80:81], v[170:171]
	v_pk_mul_f32 v[172:173], v[74:75], v[172:173]
	v_pk_mul_f32 v[174:175], v[76:77], v[174:175]
	v_pk_mul_f32 v[168:169], v[168:169], v[70:71]
	v_pk_mul_f32 v[170:171], v[170:171], v[72:73]
	v_pk_mul_f32 v[172:173], v[172:173], v[66:67]
	v_pk_mul_f32 v[174:175], v[174:175], v[68:69]
	v_cvt_pk_bf16_f32 v180, v168, v169
	v_cvt_pk_bf16_f32 v181, v170, v171
	v_cvt_pk_bf16_f32 v182, v172, v173
	v_cvt_pk_bf16_f32 v183, v174, v175
	global_store_dwordx4 v[190:191], v[180:183], off
	v_pk_mul_f32 v[160:161], v[62:63], s[98:99]
	v_pk_mul_f32 v[162:163], v[64:65], s[98:99]
	v_pk_mul_f32 v[164:165], v[58:59], s[98:99]
	v_pk_mul_f32 v[166:167], v[60:61], s[98:99]
	v_exp_f32_e32 v160, v160
	v_exp_f32_e32 v161, v161
	v_exp_f32_e32 v162, v162
	v_exp_f32_e32 v163, v163
	v_exp_f32_e32 v164, v164
	v_exp_f32_e32 v165, v165
	v_exp_f32_e32 v166, v166
	v_exp_f32_e32 v167, v167
	v_pk_add_f32 v[160:161], v[160:161], s[100:101]
	v_pk_add_f32 v[162:163], v[162:163], s[100:101]
	v_pk_add_f32 v[164:165], v[164:165], s[100:101]
	v_pk_add_f32 v[166:167], v[166:167], s[100:101]
	v_rcp_f32_e32 v160, v160
	v_rcp_f32_e32 v161, v161
	v_rcp_f32_e32 v162, v162
	v_rcp_f32_e32 v163, v163
	v_rcp_f32_e32 v164, v164
	v_rcp_f32_e32 v165, v165
	v_rcp_f32_e32 v166, v166
	v_rcp_f32_e32 v167, v167
	v_pk_mul_f32 v[160:161], v[62:63], v[160:161]
	v_pk_mul_f32 v[162:163], v[64:65], v[162:163]
	v_pk_mul_f32 v[164:165], v[58:59], v[164:165]
	v_pk_mul_f32 v[166:167], v[60:61], v[166:167]
	v_pk_mul_f32 v[160:161], v[160:161], v[54:55]
	v_pk_mul_f32 v[162:163], v[162:163], v[56:57]
	v_pk_mul_f32 v[164:165], v[164:165], v[50:51]
	v_pk_mul_f32 v[166:167], v[166:167], v[52:53]
	v_cvt_pk_bf16_f32 v176, v160, v161
	v_cvt_pk_bf16_f32 v177, v162, v163
	v_cvt_pk_bf16_f32 v178, v164, v165
	v_cvt_pk_bf16_f32 v179, v166, v167
	global_store_dwordx4 v[192:193], v[176:179], off
	v_pk_mul_f32 v[168:169], v[46:47], s[98:99]
	v_pk_mul_f32 v[170:171], v[48:49], s[98:99]
	v_pk_mul_f32 v[172:173], v[42:43], s[98:99]
	v_pk_mul_f32 v[174:175], v[44:45], s[98:99]
	v_exp_f32_e32 v168, v168
	v_exp_f32_e32 v169, v169
	v_exp_f32_e32 v170, v170
	v_exp_f32_e32 v171, v171
	v_exp_f32_e32 v172, v172
	v_exp_f32_e32 v173, v173
	v_exp_f32_e32 v174, v174
	v_exp_f32_e32 v175, v175
	v_pk_add_f32 v[168:169], v[168:169], s[100:101]
	v_pk_add_f32 v[170:171], v[170:171], s[100:101]
	v_pk_add_f32 v[172:173], v[172:173], s[100:101]
	v_pk_add_f32 v[174:175], v[174:175], s[100:101]
	v_rcp_f32_e32 v168, v168
	v_rcp_f32_e32 v169, v169
	v_rcp_f32_e32 v170, v170
	v_rcp_f32_e32 v171, v171
	v_rcp_f32_e32 v172, v172
	v_rcp_f32_e32 v173, v173
	v_rcp_f32_e32 v174, v174
	v_rcp_f32_e32 v175, v175
	v_pk_mul_f32 v[168:169], v[46:47], v[168:169]
	v_pk_mul_f32 v[170:171], v[48:49], v[170:171]
	v_pk_mul_f32 v[172:173], v[42:43], v[172:173]
	v_pk_mul_f32 v[174:175], v[44:45], v[174:175]
	v_pk_mul_f32 v[168:169], v[168:169], v[38:39]
	v_pk_mul_f32 v[170:171], v[170:171], v[40:41]
	v_pk_mul_f32 v[172:173], v[172:173], v[34:35]
	v_pk_mul_f32 v[174:175], v[174:175], v[36:37]
	v_cvt_pk_bf16_f32 v180, v168, v169
	v_cvt_pk_bf16_f32 v181, v170, v171
	v_cvt_pk_bf16_f32 v182, v172, v173
	v_cvt_pk_bf16_f32 v183, v174, v175
	global_store_dwordx4 v[194:195], v[180:183], off
	v_pk_mul_f32 v[160:161], v[30:31], s[98:99]
	v_pk_mul_f32 v[162:163], v[32:33], s[98:99]
	v_pk_mul_f32 v[164:165], v[26:27], s[98:99]
	v_pk_mul_f32 v[166:167], v[28:29], s[98:99]
	v_exp_f32_e32 v160, v160
	v_exp_f32_e32 v161, v161
	v_exp_f32_e32 v162, v162
	v_exp_f32_e32 v163, v163
	v_exp_f32_e32 v164, v164
	v_exp_f32_e32 v165, v165
	v_exp_f32_e32 v166, v166
	v_exp_f32_e32 v167, v167
	v_pk_add_f32 v[160:161], v[160:161], s[100:101]
	v_pk_add_f32 v[162:163], v[162:163], s[100:101]
	v_pk_add_f32 v[164:165], v[164:165], s[100:101]
	v_pk_add_f32 v[166:167], v[166:167], s[100:101]
	v_rcp_f32_e32 v160, v160
	v_rcp_f32_e32 v161, v161
	v_rcp_f32_e32 v162, v162
	v_rcp_f32_e32 v163, v163
	v_rcp_f32_e32 v164, v164
	v_rcp_f32_e32 v165, v165
	v_rcp_f32_e32 v166, v166
	v_rcp_f32_e32 v167, v167
	v_pk_mul_f32 v[160:161], v[30:31], v[160:161]
	v_pk_mul_f32 v[162:163], v[32:33], v[162:163]
	v_pk_mul_f32 v[164:165], v[26:27], v[164:165]
	v_pk_mul_f32 v[166:167], v[28:29], v[166:167]
	v_pk_mul_f32 v[160:161], v[160:161], v[22:23]
	v_pk_mul_f32 v[162:163], v[162:163], v[24:25]
	v_pk_mul_f32 v[164:165], v[164:165], v[18:19]
	v_pk_mul_f32 v[166:167], v[166:167], v[20:21]
	v_cvt_pk_bf16_f32 v176, v160, v161
	v_cvt_pk_bf16_f32 v177, v162, v163
	v_cvt_pk_bf16_f32 v178, v164, v165
	v_cvt_pk_bf16_f32 v179, v166, v167
	global_store_dwordx4 v[196:197], v[176:179], off
	v_pk_mul_f32 v[168:169], v[14:15], s[98:99]
	v_pk_mul_f32 v[170:171], v[16:17], s[98:99]
	v_pk_mul_f32 v[172:173], v[10:11], s[98:99]
	v_pk_mul_f32 v[174:175], v[12:13], s[98:99]
	v_exp_f32_e32 v168, v168
	v_exp_f32_e32 v169, v169
	v_exp_f32_e32 v170, v170
	v_exp_f32_e32 v171, v171
	v_exp_f32_e32 v172, v172
	v_exp_f32_e32 v173, v173
	v_exp_f32_e32 v174, v174
	v_exp_f32_e32 v175, v175
	v_pk_add_f32 v[168:169], v[168:169], s[100:101]
	v_pk_add_f32 v[170:171], v[170:171], s[100:101]
	v_pk_add_f32 v[172:173], v[172:173], s[100:101]
	v_pk_add_f32 v[174:175], v[174:175], s[100:101]
	v_rcp_f32_e32 v168, v168
	v_rcp_f32_e32 v169, v169
	v_rcp_f32_e32 v170, v170
	v_rcp_f32_e32 v171, v171
	v_rcp_f32_e32 v172, v172
	v_rcp_f32_e32 v173, v173
	v_rcp_f32_e32 v174, v174
	v_rcp_f32_e32 v175, v175
	v_pk_mul_f32 v[168:169], v[14:15], v[168:169]
	v_pk_mul_f32 v[170:171], v[16:17], v[170:171]
	v_pk_mul_f32 v[172:173], v[10:11], v[172:173]
	v_pk_mul_f32 v[174:175], v[12:13], v[174:175]
	v_pk_mul_f32 v[168:169], v[168:169], v[6:7]
	v_pk_mul_f32 v[170:171], v[170:171], v[8:9]
	v_pk_mul_f32 v[172:173], v[172:173], v[2:3]
	v_pk_mul_f32 v[174:175], v[174:175], v[4:5]
	v_cvt_pk_bf16_f32 v180, v168, v169
	v_cvt_pk_bf16_f32 v181, v170, v171
	v_cvt_pk_bf16_f32 v182, v172, v173
	v_cvt_pk_bf16_f32 v183, v174, v175
	global_store_dwordx4 v[198:199], v[180:183], off
	s_and_b64 vcc, exec, s[2:3]
	s_mov_b64 s[2:3], -1
	s_cbranch_vccnz .LBB0_1052
	s_andn2_b64 vcc, exec, s[8:9]
	s_cbranch_vccnz .LBB0_1051
	s_barrier
	s_branch .LBB0_1051

; __device__ __forceinline__ unsigned cvt_pk(float lo, float hi) { unsigned r; asm volatile("v_cvt_pk_bf16_f32 %0, %1, %2" : "=v"(r) : "v"(lo), "v"(hi)); return r; }
;     __device__ __forceinline__ void operator()(const Acc& acc, const Unit& u, int wr, int wc, int fr, int fq) const {
;         const size_t Rb = (size_t)u.pb * NT + u.pm * 256 + wr * 64 + fr; const int col0 = u.pn * 128 + wc * 32 + 8 * fq;
; #pragma unroll
;         for (int ai = 0; ai < 2; ++ai)
; #pragma unroll
;             for (int m = 0; m < 4; ++m) { bf16_t* rowp = H + (Rb + ai * 128 + m * 16) * FF + col0; f32x4 v[2];
; #pragma unroll
;                 for (int n = 0; n < 2; ++n) { const f32x4 gt = acc[ai][0][m][n], up = acc[ai][1][m][n];
; #pragma unroll
;                     for (int i = 0; i < 4; ++i) v[n][i] = gt[i] * __builtin_amdgcn_rcpf(1.f + __builtin_amdgcn_exp2f(-1.4426950408889634f * gt[i])) * up[i]; }
;                 u32x4 w; w.x = cvt_pk(v[0][0], v[0][1]); w.y = cvt_pk(v[0][2], v[0][3]); w.z = cvt_pk(v[1][0], v[1][1]); w.w = cvt_pk(v[1][2], v[1][3]); *(u32x4*)rowp = w; }
;     }
.LBB0_2087:
	s_lshl_b32 s17, s36, 8
	s_lshl_b32 s24, s24, 7
	s_ashr_i32 s19, s17, 31
	s_or_b32 s24, s24, s52
	s_add_u32 s17, s17, s51
	s_mul_i32 s5, s65, 0x900
	s_addc_u32 s19, s19, s55
	v_mov_b32_e32 v153, v146
	s_add_u32 s5, s17, s5
	s_mul_hi_i32 s4, s65, 0x900
	v_and_or_b32 v156, v153, 15, s5
	v_mov_b64_e32 v[154:155], s[10:11]
	s_addc_u32 s17, s19, s4
	v_mad_u64_u32 v[154:155], s[4:5], v156, s58, v[154:155]
	v_ashrrev_i32_e32 v152, 1, v153
	v_and_b32_e32 v152, -8, v152
	v_add_u32_e32 v152, s24, v152
	v_ashrrev_i32_e32 v153, 31, v152
	v_mad_i32_i24 v155, s17, v151, v155
	v_lshl_add_u64 v[158:159], v[152:153], 1, v[154:155]
	s_mov_b32 s98, 0xbfb8aa3b
	s_mov_b32 s99, 0xbfb8aa3b
	s_mov_b32 s100, 1.0
	s_mov_b32 s101, 1.0
	v_add_co_u32_e32 v186, vcc, 0x16000, v158
	s_nop 1
	v_addc_co_u32_e32 v187, vcc, 0, v159, vcc
	v_add_co_u32_e32 v188, vcc, 0x2c000, v158
	s_nop 1
	v_addc_co_u32_e32 v189, vcc, 0, v159, vcc
	v_add_co_u32_e32 v190, vcc, 0x42000, v158
	s_nop 1
	v_addc_co_u32_e32 v191, vcc, 0, v159, vcc
	v_add_co_u32_e32 v192, vcc, 0xb0000, v158
	s_nop 1
	v_addc_co_u32_e32 v193, vcc, 0, v159, vcc
	v_add_co_u32_e32 v194, vcc, 0xc6000, v158
	s_nop 1
	v_addc_co_u32_e32 v195, vcc, 0, v159, vcc
	v_add_co_u32_e32 v196, vcc, 0xdc000, v158
	s_nop 1
	v_addc_co_u32_e32 v197, vcc, 0, v159, vcc
	v_add_co_u32_e32 v198, vcc, 0xf2000, v158
	s_nop 1
	v_addc_co_u32_e32 v199, vcc, 0, v159, vcc
	v_pk_mul_f32 v[160:161], v[126:127], s[98:99]
	v_pk_mul_f32 v[162:163], v[128:129], s[98:99]
	v_pk_mul_f32 v[164:165], v[122:123], s[98:99]
	v_pk_mul_f32 v[166:167], v[124:125], s[98:99]
	v_exp_f32_e32 v160, v160
	v_exp_f32_e32 v161, v161
	v_exp_f32_e32 v162, v162
	v_exp_f32_e32 v163, v163
	v_exp_f32_e32 v164, v164
	v_exp_f32_e32 v165, v165
	v_exp_f32_e32 v166, v166
	v_exp_f32_e32 v167, v167
	v_pk_add_f32 v[160:161], v[160:161], s[100:101]
	v_pk_add_f32 v[162:163], v[162:163], s[100:101]
	v_pk_add_f32 v[164:165], v[164:165], s[100:101]
	v_pk_add_f32 v[166:167], v[166:167], s[100:101]
	v_rcp_f32_e32 v160, v160
	v_rcp_f32_e32 v161, v161
	v_rcp_f32_e32 v162, v162
	v_rcp_f32_e32 v163, v163
	v_rcp_f32_e32 v164, v164
	v_rcp_f32_e32 v165, v165
	v_rcp_f32_e32 v166, v166
	v_rcp_f32_e32 v167, v167
	v_pk_mul_f32 v[160:161], v[126:127], v[160:161]
	v_pk_mul_f32 v[162:163], v[128:129], v[162:163]
	v_pk_mul_f32 v[164:165], v[122:123], v[164:165]
	v_pk_mul_f32 v[166:167], v[124:125], v[166:167]
	v_pk_mul_f32 v[160:161], v[160:161], v[118:119]
	v_pk_mul_f32 v[162:163], v[162:163], v[120:121]
	v_pk_mul_f32 v[164:165], v[164:165], v[114:115]
	v_pk_mul_f32 v[166:167], v[166:167], v[116:117]
	v_cvt_pk_bf16_f32 v176, v160, v161
	v_cvt_pk_bf16_f32 v177, v162, v163
	v_cvt_pk_bf16_f32 v178, v164, v165
	v_cvt_pk_bf16_f32 v179, v166, v167
	global_store_dwordx4 v[158:159], v[176:179], off
	v_pk_mul_f32 v[168:169], v[110:111], s[98:99]
	v_pk_mul_f32 v[170:171], v[112:113], s[98:99]
	v_pk_mul_f32 v[172:173], v[106:107], s[98:99]
	v_pk_mul_f32 v[174:175], v[108:109], s[98:99]
	v_exp_f32_e32 v168, v168
	v_exp_f32_e32 v169, v169
	v_exp_f32_e32 v170, v170
	v_exp_f32_e32 v171, v171
	v_exp_f32_e32 v172, v172
	v_exp_f32_e32 v173, v173
	v_exp_f32_e32 v174, v174
	v_exp_f32_e32 v175, v175
	v_pk_add_f32 v[168:169], v[168:169], s[100:101]
	v_pk_add_f32 v[170:171], v[170:171], s[100:101]
	v_pk_add_f32 v[172:173], v[172:173], s[100:101]
	v_pk_add_f32 v[174:175], v[174:175], s[100:101]
	v_rcp_f32_e32 v168, v168
	v_rcp_f32_e32 v169, v169
	v_rcp_f32_e32 v170, v170
	v_rcp_f32_e32 v171, v171
	v_rcp_f32_e32 v172, v172
	v_rcp_f32_e32 v173, v173
	v_rcp_f32_e32 v174, v174
	v_rcp_f32_e32 v175, v175
	v_pk_mul_f32 v[168:169], v[110:111], v[168:169]
	v_pk_mul_f32 v[170:171], v[112:113], v[170:171]
	v_pk_mul_f32 v[172:173], v[106:107], v[172:173]
	v_pk_mul_f32 v[174:175], v[108:109], v[174:175]
	v_pk_mul_f32 v[168:169], v[168:169], v[102:103]
	v_pk_mul_f32 v[170:171], v[170:171], v[104:105]
	v_pk_mul_f32 v[172:173], v[172:173], v[98:99]
	v_pk_mul_f32 v[174:175], v[174:175], v[100:101]
	v_cvt_pk_bf16_f32 v180, v168, v169
	v_cvt_pk_bf16_f32 v181, v170, v171
	v_cvt_pk_bf16_f32 v182, v172, v173
	v_cvt_pk_bf16_f32 v183, v174, v175
	global_store_dwordx4 v[186:187], v[180:183], off
	v_pk_mul_f32 v[160:161], v[94:95], s[98:99]
	v_pk_mul_f32 v[162:163], v[96:97], s[98:99]
	v_pk_mul_f32 v[164:165], v[90:91], s[98:99]
	v_pk_mul_f32 v[166:167], v[92:93], s[98:99]
	v_exp_f32_e32 v160, v160
	v_exp_f32_e32 v161, v161
	v_exp_f32_e32 v162, v162
	v_exp_f32_e32 v163, v163
	v_exp_f32_e32 v164, v164
	v_exp_f32_e32 v165, v165
	v_exp_f32_e32 v166, v166
	v_exp_f32_e32 v167, v167
	v_pk_add_f32 v[160:161], v[160:161], s[100:101]
	v_pk_add_f32 v[162:163], v[162:163], s[100:101]
	v_pk_add_f32 v[164:165], v[164:165], s[100:101]
	v_pk_add_f32 v[166:167], v[166:167], s[100:101]
	v_rcp_f32_e32 v160, v160
	v_rcp_f32_e32 v161, v161
	v_rcp_f32_e32 v162, v162
	v_rcp_f32_e32 v163, v163
	v_rcp_f32_e32 v164, v164
	v_rcp_f32_e32 v165, v165
	v_rcp_f32_e32 v166, v166
	v_rcp_f32_e32 v167, v167
	v_pk_mul_f32 v[160:161], v[94:95], v[160:161]
	v_pk_mul_f32 v[162:163], v[96:97], v[162:163]
	v_pk_mul_f32 v[164:165], v[90:91], v[164:165]
	v_pk_mul_f32 v[166:167], v[92:93], v[166:167]
	v_pk_mul_f32 v[160:161], v[160:161], v[86:87]
	v_pk_mul_f32 v[162:163], v[162:163], v[88:89]
	v_pk_mul_f32 v[164:165], v[164:165], v[82:83]
	v_pk_mul_f32 v[166:167], v[166:167], v[84:85]
	v_cvt_pk_bf16_f32 v176, v160, v161
	v_cvt_pk_bf16_f32 v177, v162, v163
	v_cvt_pk_bf16_f32 v178, v164, v165
	v_cvt_pk_bf16_f32 v179, v166, v167
	global_store_dwordx4 v[188:189], v[176:179], off
	v_pk_mul_f32 v[168:169], v[78:79], s[98:99]
	v_pk_mul_f32 v[170:171], v[80:81], s[98:99]
	v_pk_mul_f32 v[172:173], v[74:75], s[98:99]
; __device__ __forceinline__ unsigned cvt_pk(float lo, float hi) { unsigned r; asm volatile("v_cvt_pk_bf16_f32 %0, %1, %2" : "=v"(r) : "v"(lo), "v"(hi)); return r; }
;     __device__ __forceinline__ void operator()(const Acc& acc, const Unit& u, int wr, int wc, int fr, int fq) const {
;     ...
;             for (int m = 0; m < 4; ++m) { bf16_t* rowp = H + (Rb + ai * 128 + m * 16) * FF + col0; f32x4 v[2];
; #pragma unroll
;                 for (int n = 0; n < 2; ++n) { const f32x4 gt = acc[ai][0][m][n], up = acc[ai][1][m][n];
; #pragma unroll
;                     for (int i = 0; i < 4; ++i) v[n][i] = gt[i] * __builtin_amdgcn_rcpf(1.f + __builtin_amdgcn_exp2f(-1.4426950408889634f * gt[i])) * up[i]; }
;                 u32x4 w; w.x = cvt_pk(v[0][0], v[0][1]); w.y = cvt_pk(v[0][2], v[0][3]); w.z = cvt_pk(v[1][0], v[1][1]); w.w = cvt_pk(v[1][2], v[1][3]); *(u32x4*)rowp = w; }
	v_pk_mul_f32 v[174:175], v[76:77], s[98:99]
	v_exp_f32_e32 v168, v168
	v_exp_f32_e32 v169, v169
	v_exp_f32_e32 v170, v170
	v_exp_f32_e32 v171, v171
	v_exp_f32_e32 v172, v172
	v_exp_f32_e32 v173, v173
	v_exp_f32_e32 v174, v174
	v_exp_f32_e32 v175, v175
	v_pk_add_f32 v[168:169], v[168:169], s[100:101]
	v_pk_add_f32 v[170:171], v[170:171], s[100:101]
	v_pk_add_f32 v[172:173], v[172:173], s[100:101]
	v_pk_add_f32 v[174:175], v[174:175], s[100:101]
	v_rcp_f32_e32 v168, v168
	v_rcp_f32_e32 v169, v169
	v_rcp_f32_e32 v170, v170
	v_rcp_f32_e32 v171, v171
	v_rcp_f32_e32 v172, v172
	v_rcp_f32_e32 v173, v173
	v_rcp_f32_e32 v174, v174
	v_rcp_f32_e32 v175, v175
	v_pk_mul_f32 v[168:169], v[78:79], v[168:169]
	v_pk_mul_f32 v[170:171], v[80:81], v[170:171]
	v_pk_mul_f32 v[172:173], v[74:75], v[172:173]
	v_pk_mul_f32 v[174:175], v[76:77], v[174:175]
	v_pk_mul_f32 v[168:169], v[168:169], v[70:71]
	v_pk_mul_f32 v[170:171], v[170:171], v[72:73]
	v_pk_mul_f32 v[172:173], v[172:173], v[66:67]
	v_pk_mul_f32 v[174:175], v[174:175], v[68:69]
	v_cvt_pk_bf16_f32 v180, v168, v169
	v_cvt_pk_bf16_f32 v181, v170, v171
	v_cvt_pk_bf16_f32 v182, v172, v173
	v_cvt_pk_bf16_f32 v183, v174, v175
	global_store_dwordx4 v[190:191], v[180:183], off
	v_pk_mul_f32 v[160:161], v[62:63], s[98:99]
	v_pk_mul_f32 v[162:163], v[64:65], s[98:99]
	v_pk_mul_f32 v[164:165], v[58:59], s[98:99]
	v_pk_mul_f32 v[166:167], v[60:61], s[98:99]
	v_exp_f32_e32 v160, v160
	v_exp_f32_e32 v161, v161
	v_exp_f32_e32 v162, v162
	v_exp_f32_e32 v163, v163
	v_exp_f32_e32 v164, v164
	v_exp_f32_e32 v165, v165
	v_exp_f32_e32 v166, v166
	v_exp_f32_e32 v167, v167
	v_pk_add_f32 v[160:161], v[160:161], s[100:101]
	v_pk_add_f32 v[162:163], v[162:163], s[100:101]
	v_pk_add_f32 v[164:165], v[164:165], s[100:101]
	v_pk_add_f32 v[166:167], v[166:167], s[100:101]
	v_rcp_f32_e32 v160, v160
	v_rcp_f32_e32 v161, v161
	v_rcp_f32_e32 v162, v162
	v_rcp_f32_e32 v163, v163
	v_rcp_f32_e32 v164, v164
	v_rcp_f32_e32 v165, v165
	v_rcp_f32_e32 v166, v166
	v_rcp_f32_e32 v167, v167
	v_pk_mul_f32 v[160:161], v[62:63], v[160:161]
	v_pk_mul_f32 v[162:163], v[64:65], v[162:163]
	v_pk_mul_f32 v[164:165], v[58:59], v[164:165]
	v_pk_mul_f32 v[166:167], v[60:61], v[166:167]
	v_pk_mul_f32 v[160:161], v[160:161], v[54:55]
	v_pk_mul_f32 v[162:163], v[162:163], v[56:57]
	v_pk_mul_f32 v[164:165], v[164:165], v[50:51]
	v_pk_mul_f32 v[166:167], v[166:167], v[52:53]
	v_cvt_pk_bf16_f32 v176, v160, v161
	v_cvt_pk_bf16_f32 v177, v162, v163
	v_cvt_pk_bf16_f32 v178, v164, v165
	v_cvt_pk_bf16_f32 v179, v166, v167
	global_store_dwordx4 v[192:193], v[176:179], off
	v_pk_mul_f32 v[168:169], v[46:47], s[98:99]
	v_pk_mul_f32 v[170:171], v[48:49], s[98:99]
	v_pk_mul_f32 v[172:173], v[42:43], s[98:99]
	v_pk_mul_f32 v[174:175], v[44:45], s[98:99]
	v_exp_f32_e32 v168, v168
	v_exp_f32_e32 v169, v169
	v_exp_f32_e32 v170, v170
	v_exp_f32_e32 v171, v171
	v_exp_f32_e32 v172, v172
	v_exp_f32_e32 v173, v173
	v_exp_f32_e32 v174, v174
	v_exp_f32_e32 v175, v175
	v_pk_add_f32 v[168:169], v[168:169], s[100:101]
	v_pk_add_f32 v[170:171], v[170:171], s[100:101]
	v_pk_add_f32 v[172:173], v[172:173], s[100:101]
	v_pk_add_f32 v[174:175], v[174:175], s[100:101]
	v_rcp_f32_e32 v168, v168
	v_rcp_f32_e32 v169, v169
	v_rcp_f32_e32 v170, v170
	v_rcp_f32_e32 v171, v171
	v_rcp_f32_e32 v172, v172
	v_rcp_f32_e32 v173, v173
	v_rcp_f32_e32 v174, v174
	v_rcp_f32_e32 v175, v175
	v_pk_mul_f32 v[168:169], v[46:47], v[168:169]
	v_pk_mul_f32 v[170:171], v[48:49], v[170:171]
	v_pk_mul_f32 v[172:173], v[42:43], v[172:173]
	v_pk_mul_f32 v[174:175], v[44:45], v[174:175]
	v_pk_mul_f32 v[168:169], v[168:169], v[38:39]
	v_pk_mul_f32 v[170:171], v[170:171], v[40:41]
	v_pk_mul_f32 v[172:173], v[172:173], v[34:35]
	v_pk_mul_f32 v[174:175], v[174:175], v[36:37]
	v_cvt_pk_bf16_f32 v180, v168, v169
	v_cvt_pk_bf16_f32 v181, v170, v171
	v_cvt_pk_bf16_f32 v182, v172, v173
	v_cvt_pk_bf16_f32 v183, v174, v175
	global_store_dwordx4 v[194:195], v[180:183], off
	v_pk_mul_f32 v[160:161], v[30:31], s[98:99]
	v_pk_mul_f32 v[162:163], v[32:33], s[98:99]
	v_pk_mul_f32 v[164:165], v[26:27], s[98:99]
	v_pk_mul_f32 v[166:167], v[28:29], s[98:99]
	v_exp_f32_e32 v160, v160
	v_exp_f32_e32 v161, v161
	v_exp_f32_e32 v162, v162
	v_exp_f32_e32 v163, v163
	v_exp_f32_e32 v164, v164
	v_exp_f32_e32 v165, v165
	v_exp_f32_e32 v166, v166
	v_exp_f32_e32 v167, v167
	v_pk_add_f32 v[160:161], v[160:161], s[100:101]
	v_pk_add_f32 v[162:163], v[162:163], s[100:101]
	v_pk_add_f32 v[164:165], v[164:165], s[100:101]
	v_pk_add_f32 v[166:167], v[166:167], s[100:101]
	v_rcp_f32_e32 v160, v160
	v_rcp_f32_e32 v161, v161
	v_rcp_f32_e32 v162, v162
	v_rcp_f32_e32 v163, v163
	v_rcp_f32_e32 v164, v164
	v_rcp_f32_e32 v165, v165
	v_rcp_f32_e32 v166, v166
	v_rcp_f32_e32 v167, v167
	v_pk_mul_f32 v[160:161], v[30:31], v[160:161]
	v_pk_mul_f32 v[162:163], v[32:33], v[162:163]
	v_pk_mul_f32 v[164:165], v[26:27], v[164:165]
	v_pk_mul_f32 v[166:167], v[28:29], v[166:167]
	v_pk_mul_f32 v[160:161], v[160:161], v[22:23]
	v_pk_mul_f32 v[162:163], v[162:163], v[24:25]
	v_pk_mul_f32 v[164:165], v[164:165], v[18:19]
	v_pk_mul_f32 v[166:167], v[166:167], v[20:21]
	v_cvt_pk_bf16_f32 v176, v160, v161
	v_cvt_pk_bf16_f32 v177, v162, v163
	v_cvt_pk_bf16_f32 v178, v164, v165
	v_cvt_pk_bf16_f32 v179, v166, v167
	global_store_dwordx4 v[196:197], v[176:179], off
	v_pk_mul_f32 v[168:169], v[14:15], s[98:99]
	v_pk_mul_f32 v[170:171], v[16:17], s[98:99]
	v_pk_mul_f32 v[172:173], v[10:11], s[98:99]
	v_pk_mul_f32 v[174:175], v[12:13], s[98:99]
	v_exp_f32_e32 v168, v168
	v_exp_f32_e32 v169, v169
	v_exp_f32_e32 v170, v170
	v_exp_f32_e32 v171, v171
	v_exp_f32_e32 v172, v172
	v_exp_f32_e32 v173, v173
	v_exp_f32_e32 v174, v174
	v_exp_f32_e32 v175, v175
	v_pk_add_f32 v[168:169], v[168:169], s[100:101]
	v_pk_add_f32 v[170:171], v[170:171], s[100:101]
	v_pk_add_f32 v[172:173], v[172:173], s[100:101]
	v_pk_add_f32 v[174:175], v[174:175], s[100:101]
	v_rcp_f32_e32 v168, v168
	v_rcp_f32_e32 v169, v169
	v_rcp_f32_e32 v170, v170
	v_rcp_f32_e32 v171, v171
	v_rcp_f32_e32 v172, v172
	v_rcp_f32_e32 v173, v173
	v_rcp_f32_e32 v174, v174
	v_rcp_f32_e32 v175, v175
	v_pk_mul_f32 v[168:169], v[14:15], v[168:169]
	v_pk_mul_f32 v[170:171], v[16:17], v[170:171]
	v_pk_mul_f32 v[172:173], v[10:11], v[172:173]
	v_pk_mul_f32 v[174:175], v[12:13], v[174:175]
	v_pk_mul_f32 v[168:169], v[168:169], v[6:7]
	v_pk_mul_f32 v[170:171], v[170:171], v[8:9]
	v_pk_mul_f32 v[172:173], v[172:173], v[2:3]
	v_pk_mul_f32 v[174:175], v[174:175], v[4:5]
	v_cvt_pk_bf16_f32 v180, v168, v169
	v_cvt_pk_bf16_f32 v181, v170, v171
	v_cvt_pk_bf16_f32 v182, v172, v173
	v_cvt_pk_bf16_f32 v183, v174, v175
	global_store_dwordx4 v[198:199], v[180:183], off
	s_and_b64 vcc, exec, s[2:3]
	s_mov_b64 s[2:3], -1
	s_cbranch_vccnz .LBB0_2078
	s_andn2_b64 vcc, exec, s[8:9]
	s_cbranch_vccnz .LBB0_2077
	s_barrier
	s_branch .LBB0_2077

; __global__ void __launch_bounds__(512, 2) mk_fwd(Args args) {
	.amdhsa_kernel _Z6mk_fwd4Args
		.amdhsa_group_segment_fixed_size 0
		.amdhsa_private_segment_fixed_size 0
		.amdhsa_kernarg_size 440
		.amdhsa_user_sgpr_count 2
		.amdhsa_user_sgpr_dispatch_ptr 0
		.amdhsa_user_sgpr_queue_ptr 0
		.amdhsa_user_sgpr_kernarg_segment_ptr 1
		.amdhsa_user_sgpr_dispatch_id 0
		.amdhsa_user_sgpr_kernarg_preload_length 0
		.amdhsa_user_sgpr_kernarg_preload_offset 0
		.amdhsa_user_sgpr_private_segment_size 0
		.amdhsa_uses_dynamic_stack 0
		.amdhsa_enable_private_segment 0
		.amdhsa_system_sgpr_workgroup_id_x 1
		.amdhsa_system_sgpr_workgroup_id_y 0
		.amdhsa_system_sgpr_workgroup_id_z 0
		.amdhsa_system_sgpr_workgroup_info 0
		.amdhsa_system_vgpr_workitem_id 2
		.amdhsa_next_free_vgpr 256
		.amdhsa_next_free_sgpr 102
		.amdhsa_accum_offset 256
		.amdhsa_reserve_vcc 1
		.amdhsa_float_round_mode_32 0
		.amdhsa_float_round_mode_16_64 0
		.amdhsa_float_denorm_mode_32 3
		.amdhsa_float_denorm_mode_16_64 3
		.amdhsa_dx10_clamp 1
		.amdhsa_ieee_mode 1
		.amdhsa_fp16_overflow 0
		.amdhsa_tg_split 0
		.amdhsa_exception_fp_ieee_invalid_op 0
		.amdhsa_exception_fp_denorm_src 0
		.amdhsa_exception_fp_ieee_div_zero 0
		.amdhsa_exception_fp_ieee_overflow 0
		.amdhsa_exception_fp_ieee_underflow 0
		.amdhsa_exception_fp_ieee_inexact 0
		.amdhsa_exception_int_div_zero 0
	.end_amdhsa_kernel

; __global__ void __launch_bounds__(512, 2) mk_fwd(Args args) {
amdhsa.kernels:
  - .agpr_count:     0
    .args:
      - .offset:         0
        .size:           184
        .value_kind:     by_value
      - .offset:         184
        .size:           4
        .value_kind:     hidden_block_count_x
      - .offset:         188
        .size:           4
        .value_kind:     hidden_block_count_y
      - .offset:         192
        .size:           4
        .value_kind:     hidden_block_count_z
      - .offset:         196
        .size:           2
        .value_kind:     hidden_group_size_x
      - .offset:         198
        .size:           2
        .value_kind:     hidden_group_size_y
      - .offset:         200
        .size:           2
        .value_kind:     hidden_group_size_z
      - .offset:         202
        .size:           2
        .value_kind:     hidden_remainder_x
      - .offset:         204
        .size:           2
        .value_kind:     hidden_remainder_y
      - .offset:         206
        .size:           2
        .value_kind:     hidden_remainder_z
      - .offset:         224
        .size:           8
        .value_kind:     hidden_global_offset_x
      - .offset:         232
        .size:           8
        .value_kind:     hidden_global_offset_y
      - .offset:         240
        .size:           8
        .value_kind:     hidden_global_offset_z
      - .offset:         248
        .size:           2
        .value_kind:     hidden_grid_dims
      - .offset:         272
        .size:           8
        .value_kind:     hidden_multigrid_sync_arg
      - .offset:         304
        .size:           4
        .value_kind:     hidden_dynamic_lds_size
    .group_segment_fixed_size: 0
    .kernarg_segment_align: 8
    .kernarg_segment_size: 440
    .language:       OpenCL C
    .language_version:
      - 2
      - 0
    .max_flat_workgroup_size: 512
    .name:           _Z6mk_fwd4Args
    .private_segment_fixed_size: 0
    .sgpr_count:     108
    .sgpr_spill_count: 19
    .symbol:         _Z6mk_fwd4Args.kd
    .uniform_work_group_size: 1
    .uses_dynamic_stack: false
    .vgpr_count:     256
    .vgpr_spill_count: 0
    .wavefront_size: 64
